# P0b shift.W bias-table GEMV loops software-prefetch the next weight row (counted vmcnt) instead of load-wait-reduce per row
# speedup vs baseline: 1.0078x; 1.0006x over previous
.LBB0_96:
	s_waitcnt vmcnt(0)
	s_or_b64 exec, exec, s[66:67]
	s_mov_b32 s8, 1
	s_andn2_b64 vcc, exec, s[62:63]
	s_mov_b64 s[62:63], 0
	s_cbranch_vccz .LBB0_107
.LBB0_97:
	s_mov_b64 s[4:5], s[26:27]
	s_mov_b64 s[68:69], s[26:27]
	s_mov_b64 s[70:71], s[26:27]
	v_mov_b32_e32 v0, v179
	s_movk_i32 s66, 0x1600
	v_ashrrev_i32_e32 v1, 6, v0
	v_add_u32_e32 v146, s89, v1
	s_mul_i32 s64, s8, 0x6c000
	s_mov_b32 s65, s9
	v_cmp_gt_i32_e32 vcc, s66, v146
	s_and_saveexec_b64 s[66:67], vcc
	s_cbranch_execz .LBB0_102
	v_and_b32_e32 v152, 63, v0
	v_lshlrev_b32_e32 v144, 6, v152
	v_lshl_add_u64 v[0:1], s[4:5], 0, v[144:145]
	v_lshl_add_u64 v[32:33], v[0:1], 0, s[64:65]
	v_add_co_u32_e32 v8, vcc, 0x100000, v32
	v_lshl_add_u64 v[12:13], v[32:33], 0, s[10:11]
	s_nop 0
	v_addc_co_u32_e32 v9, vcc, 0, v33, vcc
	v_add_co_u32_e32 v24, vcc, s2, v32
	v_lshl_add_u64 v[28:29], v[32:33], 0, s[12:13]
	s_nop 0
	v_addc_co_u32_e32 v25, vcc, 0, v33, vcc
	v_add_co_u32_e32 v40, vcc, s3, v32
	v_lshl_add_u64 v[44:45], v[32:33], 0, s[14:15]
	s_nop 0
	v_addc_co_u32_e32 v41, vcc, 0, v33, vcc
	v_add_co_u32_e32 v56, vcc, s24, v32
	v_lshl_add_u64 v[60:61], v[32:33], 0, s[16:17]
	s_nop 0
	v_addc_co_u32_e32 v57, vcc, 0, v33, vcc
	v_add_co_u32_e32 v72, vcc, s25, v32
	v_lshl_add_u64 v[76:77], v[32:33], 0, s[18:19]
	s_nop 0
	v_addc_co_u32_e32 v73, vcc, 0, v33, vcc
	v_add_co_u32_e32 v88, vcc, s33, v32
	v_lshl_add_u64 v[92:93], v[32:33], 0, s[20:21]
	s_nop 0
	v_addc_co_u32_e32 v89, vcc, 0, v33, vcc
	v_add_co_u32_e32 v104, vcc, s72, v32
	v_lshl_add_u64 v[108:109], v[32:33], 0, s[22:23]
	s_nop 0
	v_addc_co_u32_e32 v105, vcc, 0, v33, vcc
	v_add_co_u32_e32 v120, vcc, s73, v32
	v_lshl_add_u64 v[124:125], v[32:33], 0, s[28:29]
	s_nop 0
	v_addc_co_u32_e32 v121, vcc, 0, v33, vcc
	v_add_co_u32_e32 v136, vcc, s74, v32
	v_lshl_add_u64 v[140:141], v[32:33], 0, s[34:35]
	s_nop 0
	v_addc_co_u32_e32 v137, vcc, 0, v33, vcc
	global_load_dwordx4 v[0:3], v[12:13], off offset:16
	global_load_dwordx4 v[4:7], v[12:13], off offset:32
	s_nop 0
	global_load_dwordx4 v[8:11], v[8:9], off
	s_nop 0
	global_load_dwordx4 v[12:15], v[12:13], off offset:48
	s_nop 0
	global_load_dwordx4 v[16:19], v[28:29], off offset:16
	global_load_dwordx4 v[20:23], v[28:29], off offset:32
	s_nop 0
	global_load_dwordx4 v[24:27], v[24:25], off
	s_nop 0
	global_load_dwordx4 v[28:31], v[28:29], off offset:48
	s_nop 0
	global_load_dwordx4 v[32:35], v[44:45], off offset:16
	global_load_dwordx4 v[36:39], v[44:45], off offset:32
	s_nop 0
	global_load_dwordx4 v[40:43], v[40:41], off
	s_nop 0
	global_load_dwordx4 v[44:47], v[44:45], off offset:48
	s_nop 0
	global_load_dwordx4 v[48:51], v[60:61], off offset:16
	global_load_dwordx4 v[52:55], v[60:61], off offset:32
	s_nop 0
	global_load_dwordx4 v[56:59], v[56:57], off
	s_nop 0
	global_load_dwordx4 v[60:63], v[60:61], off offset:48
	s_nop 0
	global_load_dwordx4 v[64:67], v[76:77], off offset:16
	global_load_dwordx4 v[68:71], v[76:77], off offset:32
	s_nop 0
	global_load_dwordx4 v[72:75], v[72:73], off
	s_nop 0
	global_load_dwordx4 v[76:79], v[76:77], off offset:48
	s_nop 0
	global_load_dwordx4 v[80:83], v[92:93], off offset:16
	global_load_dwordx4 v[84:87], v[92:93], off offset:32
	s_nop 0
	global_load_dwordx4 v[88:91], v[88:89], off
	s_nop 0
	global_load_dwordx4 v[92:95], v[92:93], off offset:48
	s_nop 0
	global_load_dwordx4 v[96:99], v[108:109], off offset:16
	global_load_dwordx4 v[100:103], v[108:109], off offset:32
	s_nop 0
	global_load_dwordx4 v[104:107], v[104:105], off
	s_nop 0
	global_load_dwordx4 v[108:111], v[108:109], off offset:48
	s_nop 0
	global_load_dwordx4 v[112:115], v[124:125], off offset:16
	global_load_dwordx4 v[116:119], v[124:125], off offset:32
	s_nop 0
	global_load_dwordx4 v[120:123], v[120:121], off
	s_nop 0
	global_load_dwordx4 v[124:127], v[124:125], off offset:48
	s_nop 0
	global_load_dwordx4 v[128:131], v[140:141], off offset:16
	global_load_dwordx4 v[132:135], v[140:141], off offset:32
	s_nop 0
	global_load_dwordx4 v[136:139], v[136:137], off
	s_nop 0
	global_load_dwordx4 v[140:143], v[140:141], off offset:48
	v_ashrrev_i32_e32 v147, 31, v146
	s_mul_i32 s88, s8, 0x31800
	s_mul_i32 s86, s8, 0xb00000
	s_mov_b32 s87, s9
	v_lshlrev_b64 v[148:149], 11, v[146:147]
	s_add_u32 s70, s70, s88
	v_lshl_add_u64 v[150:151], s[86:87], 0, v[148:149]
	s_addc_u32 s71, s71, 0
	v_lshl_or_b32 v150, v152, 5, v150
	v_lshl_add_u64 v[148:149], v[146:147], 2, s[70:71]
	v_lshl_add_u64 v[150:151], s[68:69], 0, v[150:151]
	v_cmp_eq_u32_e64 s[4:5], 0, v152
	v_lshl_add_u64 v[148:149], v[148:149], 0, s[36:37]
	v_lshl_add_u64 v[150:151], v[150:151], 0, s[38:39]
	s_mov_b64 s[68:69], 0
	global_load_dwordx4 v[232:235], v[150:151], off
	global_load_dwordx4 v[236:239], v[150:151], off offset:16
	s_waitcnt vmcnt(0)
	s_branch .LBB0_100

.LBB0_100:
	s_waitcnt vmcnt(9)
	v_mov_b64_e32 v[152:153], v[232:233]
	v_mov_b64_e32 v[154:155], v[234:235]
	v_mov_b64_e32 v[156:157], v[236:237]
	v_mov_b64_e32 v[158:159], v[238:239]
	v_lshl_add_u64 v[240:241], v[150:151], 0, s[90:91]
	global_load_dwordx4 v[232:235], v[240:241], off
	global_load_dwordx4 v[236:239], v[240:241], off offset:16
	v_lshlrev_b32_e32 v160, 16, v152
	v_and_b32_e32 v161, 0xffff0000, v152
	v_fma_f32 v144, v8, v160, 0
	v_lshlrev_b32_e32 v162, 16, v153
	v_fmac_f32_e32 v144, v9, v161
	v_and_b32_e32 v163, 0xffff0000, v153
	v_fma_f32 v153, v56, v160, 0
	v_fmac_f32_e32 v144, v10, v162
	v_lshlrev_b32_e32 v164, 16, v154
	v_fmac_f32_e32 v153, v57, v161
	v_fmac_f32_e32 v144, v11, v163
	v_and_b32_e32 v165, 0xffff0000, v154
	v_fmac_f32_e32 v153, v58, v162
	v_fmac_f32_e32 v144, v0, v164
	v_lshlrev_b32_e32 v166, 16, v155
	v_fmac_f32_e32 v153, v59, v163
	v_fmac_f32_e32 v144, v1, v165
	v_and_b32_e32 v167, 0xffff0000, v155
	v_fmac_f32_e32 v153, v48, v164
	v_fmac_f32_e32 v144, v2, v166
	v_lshlrev_b32_e32 v168, 16, v156
	v_fmac_f32_e32 v153, v49, v165
	v_fmac_f32_e32 v144, v3, v167
	v_and_b32_e32 v169, 0xffff0000, v156
	v_fmac_f32_e32 v153, v50, v166
	v_fmac_f32_e32 v144, v4, v168
	v_lshlrev_b32_e32 v170, 16, v157
	v_fmac_f32_e32 v153, v51, v167
	v_fmac_f32_e32 v144, v5, v169
	v_and_b32_e32 v171, 0xffff0000, v157
	v_fmac_f32_e32 v153, v52, v168
	v_fmac_f32_e32 v144, v6, v170
	v_lshlrev_b32_e32 v172, 16, v158
	v_fmac_f32_e32 v153, v53, v169
	v_fmac_f32_e32 v144, v7, v171
	v_and_b32_e32 v173, 0xffff0000, v158
	v_fmac_f32_e32 v153, v54, v170
	v_fmac_f32_e32 v144, v12, v172
	v_lshlrev_b32_e32 v174, 16, v159
	v_fmac_f32_e32 v153, v55, v171
	v_fmac_f32_e32 v144, v13, v173
	v_and_b32_e32 v175, 0xffff0000, v159
	v_fmac_f32_e32 v153, v60, v172
	v_fmac_f32_e32 v144, v14, v174
	v_fmac_f32_e32 v153, v61, v173
	v_fmac_f32_e32 v144, v15, v175
	v_fmac_f32_e32 v153, v62, v174
	v_fmac_f32_e32 v153, v63, v175
	v_add_f32_dpp v144, v144, v144 quad_perm:[1,0,3,2] row_mask:0xf bank_mask:0xf bound_ctrl:1
	v_fma_f32 v147, v24, v160, 0
	v_add_f32_dpp v153, v153, v153 quad_perm:[1,0,3,2] row_mask:0xf bank_mask:0xf bound_ctrl:1
	v_add_f32_dpp v144, v144, v144 quad_perm:[2,3,0,1] row_mask:0xf bank_mask:0xf bound_ctrl:1
	v_fmac_f32_e32 v147, v25, v161
	v_add_f32_dpp v153, v153, v153 quad_perm:[2,3,0,1] row_mask:0xf bank_mask:0xf bound_ctrl:1
	v_add_f32_dpp v144, v144, v144 row_half_mirror row_mask:0xf bank_mask:0xf bound_ctrl:1
	v_fmac_f32_e32 v147, v26, v162
	v_add_f32_dpp v153, v153, v153 row_half_mirror row_mask:0xf bank_mask:0xf bound_ctrl:1
	v_add_f32_dpp v144, v144, v144 row_mirror row_mask:0xf bank_mask:0xf bound_ctrl:1
	v_mov_b32_e32 v154, v144
	s_nop 1
	v_permlane16_swap_b32_e32 v144, v154
	v_add_f32_dpp v153, v153, v153 row_mirror row_mask:0xf bank_mask:0xf bound_ctrl:1
	v_add_f32_e32 v144, v144, v154
	v_mov_b32_e32 v154, v153
	s_nop 1
	v_permlane16_swap_b32_e32 v153, v154
	v_add_f32_e32 v153, v153, v154
	v_fma_f32 v154, v72, v160, 0
	v_fmac_f32_e32 v147, v27, v163
	v_fmac_f32_e32 v154, v73, v161
	v_fmac_f32_e32 v147, v16, v164
	v_fmac_f32_e32 v154, v74, v162
	v_fmac_f32_e32 v147, v17, v165
	v_fmac_f32_e32 v154, v75, v163
	v_fmac_f32_e32 v147, v18, v166
	v_fmac_f32_e32 v154, v64, v164
	v_fmac_f32_e32 v147, v19, v167
	v_fmac_f32_e32 v154, v65, v165
	v_fmac_f32_e32 v147, v20, v168
	v_fmac_f32_e32 v154, v66, v166
	v_fmac_f32_e32 v147, v21, v169
	v_fmac_f32_e32 v154, v67, v167
	v_fmac_f32_e32 v147, v22, v170
	v_fmac_f32_e32 v154, v68, v168
	v_fmac_f32_e32 v147, v23, v171
	v_fmac_f32_e32 v154, v69, v169
	v_fmac_f32_e32 v147, v28, v172
	v_fmac_f32_e32 v154, v70, v170
	v_fmac_f32_e32 v147, v29, v173
	v_fmac_f32_e32 v154, v71, v171
	v_fmac_f32_e32 v147, v30, v174
	v_fmac_f32_e32 v154, v76, v172
	v_fmac_f32_e32 v147, v31, v175
	v_fmac_f32_e32 v154, v77, v173
	v_fmac_f32_e32 v154, v78, v174
	v_add_f32_dpp v147, v147, v147 quad_perm:[1,0,3,2] row_mask:0xf bank_mask:0xf bound_ctrl:1
	v_fmac_f32_e32 v154, v79, v175
	v_fma_f32 v152, v40, v160, 0
	v_add_f32_dpp v147, v147, v147 quad_perm:[2,3,0,1] row_mask:0xf bank_mask:0xf bound_ctrl:1
	v_add_f32_dpp v154, v154, v154 quad_perm:[1,0,3,2] row_mask:0xf bank_mask:0xf bound_ctrl:1
	v_fmac_f32_e32 v152, v41, v161
	v_add_f32_dpp v147, v147, v147 row_half_mirror row_mask:0xf bank_mask:0xf bound_ctrl:1
	v_add_f32_dpp v154, v154, v154 quad_perm:[2,3,0,1] row_mask:0xf bank_mask:0xf bound_ctrl:1
	v_fmac_f32_e32 v152, v42, v162
	v_add_f32_dpp v147, v147, v147 row_mirror row_mask:0xf bank_mask:0xf bound_ctrl:1
	v_mov_b32_e32 v155, v147
	v_add_f32_dpp v154, v154, v154 row_half_mirror row_mask:0xf bank_mask:0xf bound_ctrl:1
	s_nop 0
	v_permlane16_swap_b32_e32 v147, v155
	v_add_f32_dpp v154, v154, v154 row_mirror row_mask:0xf bank_mask:0xf bound_ctrl:1
	v_add_f32_e32 v147, v147, v155
	v_mov_b32_e32 v155, v154
	s_nop 1
	v_permlane16_swap_b32_e32 v154, v155
	v_add_f32_e32 v154, v154, v155
	v_fma_f32 v155, v88, v160, 0
	v_fmac_f32_e32 v152, v43, v163
	v_fmac_f32_e32 v155, v89, v161
	v_fmac_f32_e32 v152, v32, v164
	v_fmac_f32_e32 v155, v90, v162
	v_fmac_f32_e32 v152, v33, v165
	v_fmac_f32_e32 v155, v91, v163
	v_fmac_f32_e32 v152, v34, v166
	v_fmac_f32_e32 v155, v80, v164
	v_fmac_f32_e32 v152, v35, v167
	v_fmac_f32_e32 v155, v81, v165
	v_fmac_f32_e32 v152, v36, v168
	v_fmac_f32_e32 v155, v82, v166
	v_fmac_f32_e32 v152, v37, v169
	v_fmac_f32_e32 v155, v83, v167
	v_fmac_f32_e32 v152, v38, v170
	v_fmac_f32_e32 v155, v84, v168
	v_fmac_f32_e32 v152, v39, v171
	v_fmac_f32_e32 v155, v85, v169
	v_fmac_f32_e32 v152, v44, v172
	v_fmac_f32_e32 v155, v86, v170
	v_fmac_f32_e32 v152, v45, v173
	v_fmac_f32_e32 v155, v87, v171
	v_fmac_f32_e32 v152, v46, v174
	v_fmac_f32_e32 v155, v92, v172
	v_fmac_f32_e32 v152, v47, v175
	v_fmac_f32_e32 v155, v93, v173
	v_fmac_f32_e32 v155, v94, v174
	v_add_f32_dpp v152, v152, v152 quad_perm:[1,0,3,2] row_mask:0xf bank_mask:0xf bound_ctrl:1
	v_fmac_f32_e32 v155, v95, v175
	v_fma_f32 v176, v136, v160, 0
	v_add_f32_dpp v152, v152, v152 quad_perm:[2,3,0,1] row_mask:0xf bank_mask:0xf bound_ctrl:1
	v_add_f32_dpp v155, v155, v155 quad_perm:[1,0,3,2] row_mask:0xf bank_mask:0xf bound_ctrl:1
	v_fmac_f32_e32 v176, v137, v161
	v_add_f32_dpp v152, v152, v152 row_half_mirror row_mask:0xf bank_mask:0xf bound_ctrl:1
	v_add_f32_dpp v155, v155, v155 quad_perm:[2,3,0,1] row_mask:0xf bank_mask:0xf bound_ctrl:1
	v_fmac_f32_e32 v176, v138, v162
	v_add_f32_dpp v152, v152, v152 row_mirror row_mask:0xf bank_mask:0xf bound_ctrl:1
	v_mov_b32_e32 v156, v152
	v_add_f32_dpp v155, v155, v155 row_half_mirror row_mask:0xf bank_mask:0xf bound_ctrl:1
	s_nop 0
	v_permlane16_swap_b32_e32 v152, v156
	v_add_f32_dpp v155, v155, v155 row_mirror row_mask:0xf bank_mask:0xf bound_ctrl:1
	v_add_f32_e32 v152, v152, v156
	v_mov_b32_e32 v156, v155
	s_nop 1
	v_permlane16_swap_b32_e32 v155, v156
	v_add_f32_e32 v155, v155, v156
	v_fma_f32 v156, v104, v160, 0
	v_fmac_f32_e32 v156, v105, v161
	v_fmac_f32_e32 v156, v106, v162
	v_fmac_f32_e32 v156, v107, v163
	v_fmac_f32_e32 v156, v96, v164
	v_fmac_f32_e32 v156, v97, v165
	v_fmac_f32_e32 v156, v98, v166
	v_fmac_f32_e32 v156, v99, v167
	v_fmac_f32_e32 v156, v100, v168
	v_fmac_f32_e32 v156, v101, v169
	v_fmac_f32_e32 v156, v102, v170
	v_fmac_f32_e32 v156, v103, v171
	v_fmac_f32_e32 v156, v108, v172
	v_fmac_f32_e32 v156, v109, v173
	v_fmac_f32_e32 v156, v110, v174
	v_fmac_f32_e32 v156, v111, v175
	v_fmac_f32_e32 v176, v139, v163
	v_fmac_f32_e32 v176, v128, v164
	v_add_f32_dpp v156, v156, v156 quad_perm:[1,0,3,2] row_mask:0xf bank_mask:0xf bound_ctrl:1
	v_fmac_f32_e32 v176, v129, v165
	v_fmac_f32_e32 v176, v130, v166
	v_add_f32_dpp v156, v156, v156 quad_perm:[2,3,0,1] row_mask:0xf bank_mask:0xf bound_ctrl:1
	v_fmac_f32_e32 v176, v131, v167
	v_fmac_f32_e32 v176, v132, v168
	v_add_f32_dpp v156, v156, v156 row_half_mirror row_mask:0xf bank_mask:0xf bound_ctrl:1
	v_fmac_f32_e32 v176, v133, v169
	v_fmac_f32_e32 v176, v134, v170
	v_add_f32_dpp v156, v156, v156 row_mirror row_mask:0xf bank_mask:0xf bound_ctrl:1
	v_mov_b32_e32 v157, v156
	s_nop 1
	v_permlane16_swap_b32_e32 v156, v157
	v_add_f32_e32 v156, v156, v157
	v_fma_f32 v157, v120, v160, 0
	v_fmac_f32_e32 v157, v121, v161
	v_fmac_f32_e32 v157, v122, v162
	v_fmac_f32_e32 v157, v123, v163
	v_fmac_f32_e32 v157, v112, v164
	v_fmac_f32_e32 v157, v113, v165
	v_fmac_f32_e32 v157, v114, v166
	v_fmac_f32_e32 v157, v115, v167
	v_fmac_f32_e32 v157, v116, v168
	v_fmac_f32_e32 v157, v117, v169
	v_fmac_f32_e32 v157, v118, v170
	v_fmac_f32_e32 v157, v119, v171
	v_fmac_f32_e32 v176, v135, v171
	v_fmac_f32_e32 v157, v124, v172
	v_fmac_f32_e32 v176, v140, v172
	v_fmac_f32_e32 v157, v125, v173
	v_fmac_f32_e32 v176, v141, v173
	v_fmac_f32_e32 v157, v126, v174
	v_fmac_f32_e32 v176, v142, v174
	v_fmac_f32_e32 v157, v127, v175
	v_fmac_f32_e32 v176, v143, v175
	v_mov_b32_e32 v159, v147
	v_add_f32_dpp v157, v157, v157 quad_perm:[1,0,3,2] row_mask:0xf bank_mask:0xf bound_ctrl:1
	v_add_f32_dpp v166, v176, v176 quad_perm:[1,0,3,2] row_mask:0xf bank_mask:0xf bound_ctrl:1
	v_mov_b32_e32 v160, v152
	v_add_f32_dpp v157, v157, v157 quad_perm:[2,3,0,1] row_mask:0xf bank_mask:0xf bound_ctrl:1
	v_add_f32_dpp v166, v166, v166 quad_perm:[2,3,0,1] row_mask:0xf bank_mask:0xf bound_ctrl:1
	v_mov_b32_e32 v161, v153
	v_add_f32_dpp v157, v157, v157 row_half_mirror row_mask:0xf bank_mask:0xf bound_ctrl:1
	v_add_f32_dpp v166, v166, v166 row_half_mirror row_mask:0xf bank_mask:0xf bound_ctrl:1
	v_mov_b32_e32 v162, v154
	v_add_f32_dpp v157, v157, v157 row_mirror row_mask:0xf bank_mask:0xf bound_ctrl:1
	v_add_f32_dpp v166, v166, v166 row_mirror row_mask:0xf bank_mask:0xf bound_ctrl:1
	v_mov_b32_e32 v158, v157
	v_mov_b32_e32 v167, v166
	s_nop 0
	v_permlane16_swap_b32_e32 v157, v158
	v_permlane16_swap_b32_e32 v166, v167
	v_add_f32_e32 v157, v157, v158
	v_add_f32_e32 v166, v166, v167
	v_mov_b32_e32 v158, v144
	v_mov_b32_e32 v163, v155
	v_mov_b32_e32 v164, v156
	v_mov_b32_e32 v165, v157
	v_mov_b32_e32 v167, v166
	v_permlane32_swap_b32_e32 v144, v158
	v_permlane32_swap_b32_e32 v147, v159
	v_permlane32_swap_b32_e32 v152, v160
	v_permlane32_swap_b32_e32 v153, v161
	v_permlane32_swap_b32_e32 v154, v162
	v_permlane32_swap_b32_e32 v155, v163
	v_permlane32_swap_b32_e32 v156, v164
	v_permlane32_swap_b32_e32 v157, v165
	v_permlane32_swap_b32_e32 v166, v167
	s_and_saveexec_b64 s[70:71], s[4:5]
	s_cbranch_execz .LBB0_99
	v_add_f32_e32 v160, v152, v160
	v_add_co_u32_e32 v152, vcc, 0xfffd4000, v148
	v_add_f32_e32 v161, v153, v161
	v_add_f32_e32 v144, v144, v158
	v_addc_co_u32_e32 v153, vcc, -1, v149, vcc
	global_store_dword v[152:153], v144, off
	v_add_co_u32_e32 v152, vcc, 0xfffda000, v148
	v_add_f32_e32 v147, v147, v159
	s_nop 0
	v_addc_co_u32_e32 v153, vcc, -1, v149, vcc
	global_store_dword v[152:153], v147, off offset:-2048
	v_add_co_u32_e32 v152, vcc, 0xfffdf000, v148
	v_add_f32_e32 v154, v154, v162
	s_nop 0
	v_addc_co_u32_e32 v153, vcc, -1, v149, vcc
	global_store_dword v[152:153], v160, off
	v_add_co_u32_e32 v152, vcc, 0xfffe5000, v148
	v_add_f32_e32 v155, v155, v163
	s_nop 0
	v_addc_co_u32_e32 v153, vcc, -1, v149, vcc
	global_store_dword v[152:153], v161, off offset:-2048
	v_add_co_u32_e32 v152, vcc, 0xfffea000, v148
	v_add_f32_e32 v156, v156, v164
	s_nop 0
	v_addc_co_u32_e32 v153, vcc, -1, v149, vcc
	global_store_dword v[152:153], v154, off
	v_add_co_u32_e32 v152, vcc, 0xffff0000, v148
	v_add_f32_e32 v157, v157, v165
	s_nop 0
	v_addc_co_u32_e32 v153, vcc, -1, v149, vcc
	global_store_dword v[152:153], v155, off offset:-2048
	v_add_co_u32_e32 v152, vcc, 0xffff5000, v148
	v_add_f32_e32 v166, v166, v167
	s_nop 0
	v_addc_co_u32_e32 v153, vcc, -1, v149, vcc
	global_store_dword v[152:153], v156, off
	v_add_co_u32_e32 v152, vcc, 0xffffb000, v148
	s_nop 1
	v_addc_co_u32_e32 v153, vcc, -1, v149, vcc
	global_store_dword v[152:153], v157, off offset:-2048
	global_store_dword v[148:149], v166, off
	s_branch .LBB0_99
.LBB0_102:
	s_waitcnt vmcnt(0)
	s_or_b64 exec, exec, s[66:67]
	s_mov_b64 s[4:5], s[26:27]
	s_mov_b64 s[68:69], s[26:27]
	s_mov_b64 s[70:71], s[26:27]
	v_mov_b32_e32 v0, v179
	s_xor_b64 s[62:63], s[62:63], -1
	v_ashrrev_i32_e32 v1, 6, v0
	v_add_u32_e32 v146, s89, v1
	v_cmp_gt_i32_e32 vcc, s76, v146
	s_and_saveexec_b64 s[66:67], vcc
	s_cbranch_execz .LBB0_96
	v_and_b32_e32 v152, 63, v0
	v_lshlrev_b32_e32 v144, 6, v152
	v_lshl_add_u64 v[0:1], s[4:5], 0, v[144:145]
	v_lshl_add_u64 v[128:129], v[0:1], 0, s[64:65]
	v_add_co_u32_e32 v8, vcc, 0x136000, v128
	v_lshl_add_u64 v[12:13], v[128:129], 0, s[40:41]
	s_nop 0
	v_addc_co_u32_e32 v9, vcc, 0, v129, vcc
	v_add_co_u32_e32 v24, vcc, s77, v128
	v_lshl_add_u64 v[28:29], v[128:129], 0, s[42:43]
	s_nop 0
	v_addc_co_u32_e32 v25, vcc, 0, v129, vcc
	v_add_co_u32_e32 v40, vcc, s78, v128
	v_lshl_add_u64 v[44:45], v[128:129], 0, s[44:45]
	s_nop 0
	v_addc_co_u32_e32 v41, vcc, 0, v129, vcc
	v_add_co_u32_e32 v56, vcc, s79, v128
	v_lshl_add_u64 v[60:61], v[128:129], 0, s[46:47]
	s_nop 0
	v_addc_co_u32_e32 v57, vcc, 0, v129, vcc
	v_add_co_u32_e32 v72, vcc, s80, v128
	v_lshl_add_u64 v[76:77], v[128:129], 0, s[48:49]
	s_nop 0
	v_addc_co_u32_e32 v73, vcc, 0, v129, vcc
	v_add_co_u32_e32 v88, vcc, s81, v128
	v_lshl_add_u64 v[92:93], v[128:129], 0, s[50:51]
	s_nop 0
	v_addc_co_u32_e32 v89, vcc, 0, v129, vcc
	v_add_co_u32_e32 v104, vcc, s82, v128
	v_lshl_add_u64 v[108:109], v[128:129], 0, s[52:53]
	s_nop 0
	v_addc_co_u32_e32 v105, vcc, 0, v129, vcc
	v_add_co_u32_e32 v120, vcc, s83, v128
	v_lshl_add_u64 v[124:125], v[128:129], 0, s[54:55]
	s_nop 0
	v_addc_co_u32_e32 v121, vcc, 0, v129, vcc
	v_add_co_u32_e32 v136, vcc, s84, v128
	v_lshl_add_u64 v[140:141], v[128:129], 0, s[56:57]
	s_nop 0
	v_addc_co_u32_e32 v137, vcc, 0, v129, vcc
	global_load_dwordx4 v[0:3], v[12:13], off offset:16
	global_load_dwordx4 v[4:7], v[12:13], off offset:32
	s_nop 0
	global_load_dwordx4 v[8:11], v[8:9], off
	s_nop 0
	global_load_dwordx4 v[12:15], v[12:13], off offset:48
	s_nop 0
	global_load_dwordx4 v[16:19], v[28:29], off offset:16
	global_load_dwordx4 v[20:23], v[28:29], off offset:32
	s_nop 0
	global_load_dwordx4 v[24:27], v[24:25], off
	s_nop 0
	global_load_dwordx4 v[28:31], v[28:29], off offset:48
	s_nop 0
	global_load_dwordx4 v[32:35], v[44:45], off offset:16
	global_load_dwordx4 v[36:39], v[44:45], off offset:32
	s_nop 0
	global_load_dwordx4 v[40:43], v[40:41], off
	s_nop 0
	global_load_dwordx4 v[44:47], v[44:45], off offset:48
	s_nop 0
	global_load_dwordx4 v[48:51], v[60:61], off offset:16
	global_load_dwordx4 v[52:55], v[60:61], off offset:32
	s_nop 0
	global_load_dwordx4 v[56:59], v[56:57], off
	s_nop 0
	global_load_dwordx4 v[60:63], v[60:61], off offset:48
	s_nop 0
	global_load_dwordx4 v[64:67], v[76:77], off offset:16
	global_load_dwordx4 v[68:71], v[76:77], off offset:32
	s_nop 0
	global_load_dwordx4 v[72:75], v[72:73], off
	s_nop 0
	global_load_dwordx4 v[76:79], v[76:77], off offset:48
	s_nop 0
	global_load_dwordx4 v[80:83], v[92:93], off offset:16
	global_load_dwordx4 v[84:87], v[92:93], off offset:32
	s_nop 0
	global_load_dwordx4 v[88:91], v[88:89], off
	s_nop 0
	global_load_dwordx4 v[92:95], v[92:93], off offset:48
	s_nop 0
	global_load_dwordx4 v[96:99], v[108:109], off offset:16
	global_load_dwordx4 v[100:103], v[108:109], off offset:32
	s_nop 0
	global_load_dwordx4 v[104:107], v[104:105], off
	s_nop 0
	global_load_dwordx4 v[108:111], v[108:109], off offset:48
	s_nop 0
	global_load_dwordx4 v[112:115], v[124:125], off offset:16
	global_load_dwordx4 v[116:119], v[124:125], off offset:32
	s_nop 0
	global_load_dwordx4 v[120:123], v[120:121], off
	s_nop 0
	global_load_dwordx4 v[124:127], v[124:125], off offset:48
	s_nop 0
	global_load_dwordx4 v[128:131], v[140:141], off offset:16
	global_load_dwordx4 v[132:135], v[140:141], off offset:32
	s_nop 0
	global_load_dwordx4 v[136:139], v[136:137], off
	s_nop 0
	global_load_dwordx4 v[140:143], v[140:141], off offset:48
	v_ashrrev_i32_e32 v147, 31, v146
	s_mul_i32 s86, s8, 0x12000
	s_lshl_b64 s[64:65], s[8:9], 22
	v_lshlrev_b64 v[150:151], 11, v[146:147]
	s_add_u32 s70, s70, s86
	v_lshl_add_u64 v[150:151], s[64:65], 0, v[150:151]
	s_addc_u32 s71, s71, 0
	v_lshl_or_b32 v150, v152, 5, v150
	v_lshl_add_u64 v[148:149], v[146:147], 2, s[70:71]
	v_lshl_add_u64 v[150:151], s[68:69], 0, v[150:151]
	v_cmp_eq_u32_e64 s[4:5], 0, v152
	v_lshl_add_u64 v[148:149], v[148:149], 0, s[58:59]
	v_lshl_add_u64 v[150:151], v[150:151], 0, s[60:61]
	s_mov_b64 s[64:65], 0
	global_load_dwordx4 v[232:235], v[150:151], off
	global_load_dwordx4 v[236:239], v[150:151], off offset:16
	s_waitcnt vmcnt(0)
	s_branch .LBB0_105

.LBB0_105:
	s_waitcnt vmcnt(9)
	v_mov_b64_e32 v[152:153], v[232:233]
	v_mov_b64_e32 v[154:155], v[234:235]
	v_mov_b64_e32 v[156:157], v[236:237]
	v_mov_b64_e32 v[158:159], v[238:239]
	v_lshl_add_u64 v[240:241], v[150:151], 0, s[90:91]
	global_load_dwordx4 v[232:235], v[240:241], off
	global_load_dwordx4 v[236:239], v[240:241], off offset:16
	v_lshlrev_b32_e32 v166, 16, v152
	v_and_b32_e32 v167, 0xffff0000, v152
	v_lshlrev_b32_e32 v174, 16, v156
	v_and_b32_e32 v175, 0xffff0000, v156
	v_lshlrev_b32_e32 v178, 16, v158
	v_and_b32_e32 v180, 0xffff0000, v158
	v_fma_f32 v144, v8, v166, 0
	v_fma_f32 v147, v24, v166, 0
	v_fma_f32 v152, v40, v166, 0
	v_fma_f32 v156, v56, v166, 0
	v_fma_f32 v158, v72, v166, 0
	v_fma_f32 v160, v88, v166, 0
	v_fma_f32 v162, v104, v166, 0
	v_fma_f32 v164, v120, v166, 0
	v_fma_f32 v166, v136, v166, 0
	v_lshlrev_b32_e32 v168, 16, v153
	v_fmac_f32_e32 v144, v9, v167
	v_fmac_f32_e32 v147, v25, v167
	v_fmac_f32_e32 v152, v41, v167
	v_fmac_f32_e32 v156, v57, v167
	v_fmac_f32_e32 v158, v73, v167
	v_fmac_f32_e32 v160, v89, v167
	v_fmac_f32_e32 v162, v105, v167
	v_fmac_f32_e32 v164, v121, v167
	v_fmac_f32_e32 v166, v137, v167
	v_and_b32_e32 v169, 0xffff0000, v153
	v_fmac_f32_e32 v144, v10, v168
	v_fmac_f32_e32 v147, v26, v168
	v_fmac_f32_e32 v152, v42, v168
	v_fmac_f32_e32 v156, v58, v168
	v_fmac_f32_e32 v158, v74, v168
	v_fmac_f32_e32 v160, v90, v168
	v_fmac_f32_e32 v162, v106, v168
	v_fmac_f32_e32 v164, v122, v168
	v_fmac_f32_e32 v166, v138, v168
	v_lshlrev_b32_e32 v170, 16, v154
	v_fmac_f32_e32 v144, v11, v169
	v_fmac_f32_e32 v147, v27, v169
	v_fmac_f32_e32 v152, v43, v169
	v_fmac_f32_e32 v156, v59, v169
	v_fmac_f32_e32 v158, v75, v169
	v_fmac_f32_e32 v160, v91, v169
	v_fmac_f32_e32 v162, v107, v169
	v_fmac_f32_e32 v164, v123, v169
	v_fmac_f32_e32 v166, v139, v169
	v_and_b32_e32 v171, 0xffff0000, v154
	v_fmac_f32_e32 v144, v0, v170
	v_fmac_f32_e32 v147, v16, v170
	v_fmac_f32_e32 v152, v32, v170
	v_fmac_f32_e32 v156, v48, v170
	v_fmac_f32_e32 v158, v64, v170
	v_fmac_f32_e32 v160, v80, v170
	v_fmac_f32_e32 v162, v96, v170
	v_fmac_f32_e32 v164, v112, v170
	v_fmac_f32_e32 v166, v128, v170
	v_lshlrev_b32_e32 v172, 16, v155
	v_fmac_f32_e32 v144, v1, v171
	v_fmac_f32_e32 v147, v17, v171
	v_fmac_f32_e32 v152, v33, v171
	v_fmac_f32_e32 v156, v49, v171
	v_fmac_f32_e32 v158, v65, v171
	v_fmac_f32_e32 v160, v81, v171
	v_fmac_f32_e32 v162, v97, v171
	v_fmac_f32_e32 v164, v113, v171
	v_fmac_f32_e32 v166, v129, v171
	v_and_b32_e32 v173, 0xffff0000, v155
	v_fmac_f32_e32 v144, v2, v172
	v_fmac_f32_e32 v147, v18, v172
	v_fmac_f32_e32 v152, v34, v172
	v_fmac_f32_e32 v156, v50, v172
	v_fmac_f32_e32 v158, v66, v172
	v_fmac_f32_e32 v160, v82, v172
	v_fmac_f32_e32 v162, v98, v172
	v_fmac_f32_e32 v164, v114, v172
	v_fmac_f32_e32 v166, v130, v172
	v_fmac_f32_e32 v144, v3, v173
	v_fmac_f32_e32 v147, v19, v173
	v_fmac_f32_e32 v152, v35, v173
	v_fmac_f32_e32 v156, v51, v173
	v_fmac_f32_e32 v158, v67, v173
	v_fmac_f32_e32 v160, v83, v173
	v_fmac_f32_e32 v162, v99, v173
	v_fmac_f32_e32 v164, v115, v173
	v_fmac_f32_e32 v166, v131, v173
	v_fmac_f32_e32 v144, v4, v174
	v_fmac_f32_e32 v147, v20, v174
	v_fmac_f32_e32 v152, v36, v174
	v_fmac_f32_e32 v156, v52, v174
	v_fmac_f32_e32 v158, v68, v174
	v_fmac_f32_e32 v160, v84, v174
	v_fmac_f32_e32 v162, v100, v174
	v_fmac_f32_e32 v164, v116, v174
	v_fmac_f32_e32 v166, v132, v174
	v_lshlrev_b32_e32 v176, 16, v157
	v_fmac_f32_e32 v144, v5, v175
	v_fmac_f32_e32 v147, v21, v175
	v_fmac_f32_e32 v152, v37, v175
	v_fmac_f32_e32 v156, v53, v175
	v_fmac_f32_e32 v158, v69, v175
	v_fmac_f32_e32 v160, v85, v175
	v_fmac_f32_e32 v162, v101, v175
	v_fmac_f32_e32 v164, v117, v175
	v_fmac_f32_e32 v166, v133, v175
	v_and_b32_e32 v177, 0xffff0000, v157
	v_fmac_f32_e32 v144, v6, v176
	v_fmac_f32_e32 v147, v22, v176
	v_fmac_f32_e32 v152, v38, v176
	v_fmac_f32_e32 v156, v54, v176
	v_fmac_f32_e32 v158, v70, v176
	v_fmac_f32_e32 v160, v86, v176
	v_fmac_f32_e32 v162, v102, v176
	v_fmac_f32_e32 v164, v118, v176
	v_fmac_f32_e32 v166, v134, v176
	v_fmac_f32_e32 v144, v7, v177
	v_fmac_f32_e32 v147, v23, v177
	v_fmac_f32_e32 v152, v39, v177
	v_fmac_f32_e32 v156, v55, v177
	v_fmac_f32_e32 v158, v71, v177
	v_fmac_f32_e32 v160, v87, v177
	v_fmac_f32_e32 v162, v103, v177
	v_fmac_f32_e32 v164, v119, v177
	v_fmac_f32_e32 v166, v135, v177
	v_fmac_f32_e32 v144, v12, v178
	v_fmac_f32_e32 v147, v28, v178
	v_fmac_f32_e32 v152, v44, v178
	v_fmac_f32_e32 v156, v60, v178
	v_fmac_f32_e32 v158, v76, v178
	v_fmac_f32_e32 v160, v92, v178
	v_fmac_f32_e32 v162, v108, v178
	v_fmac_f32_e32 v164, v124, v178
	v_fmac_f32_e32 v166, v140, v178
	v_lshlrev_b32_e32 v181, 16, v159
	v_fmac_f32_e32 v144, v13, v180
	v_fmac_f32_e32 v147, v29, v180
	v_fmac_f32_e32 v152, v45, v180
	v_fmac_f32_e32 v156, v61, v180
	v_fmac_f32_e32 v158, v77, v180
	v_fmac_f32_e32 v160, v93, v180
	v_fmac_f32_e32 v162, v109, v180
	v_fmac_f32_e32 v164, v125, v180
	v_fmac_f32_e32 v166, v141, v180
	v_and_b32_e32 v182, 0xffff0000, v159
	v_fmac_f32_e32 v144, v14, v181
	v_fmac_f32_e32 v147, v30, v181
	v_fmac_f32_e32 v152, v46, v181
	v_fmac_f32_e32 v156, v62, v181
	v_fmac_f32_e32 v158, v78, v181
	v_fmac_f32_e32 v160, v94, v181
	v_fmac_f32_e32 v162, v110, v181
	v_fmac_f32_e32 v164, v126, v181
	v_fmac_f32_e32 v166, v142, v181
	v_fmac_f32_e32 v144, v15, v182
	v_fmac_f32_e32 v147, v31, v182
	v_fmac_f32_e32 v152, v47, v182
	v_fmac_f32_e32 v156, v63, v182
	v_fmac_f32_e32 v158, v79, v182
	v_fmac_f32_e32 v160, v95, v182
	v_fmac_f32_e32 v162, v111, v182
	v_fmac_f32_e32 v164, v127, v182
	v_fmac_f32_e32 v166, v143, v182
	v_add_f32_dpp v144, v144, v144 quad_perm:[1,0,3,2] row_mask:0xf bank_mask:0xf bound_ctrl:1
	v_add_f32_dpp v147, v147, v147 quad_perm:[1,0,3,2] row_mask:0xf bank_mask:0xf bound_ctrl:1
	v_add_f32_dpp v152, v152, v152 quad_perm:[1,0,3,2] row_mask:0xf bank_mask:0xf bound_ctrl:1
	v_add_f32_dpp v156, v156, v156 quad_perm:[1,0,3,2] row_mask:0xf bank_mask:0xf bound_ctrl:1
	v_add_f32_dpp v158, v158, v158 quad_perm:[1,0,3,2] row_mask:0xf bank_mask:0xf bound_ctrl:1
	v_add_f32_dpp v160, v160, v160 quad_perm:[1,0,3,2] row_mask:0xf bank_mask:0xf bound_ctrl:1
	v_add_f32_dpp v162, v162, v162 quad_perm:[1,0,3,2] row_mask:0xf bank_mask:0xf bound_ctrl:1
	v_add_f32_dpp v164, v164, v164 quad_perm:[1,0,3,2] row_mask:0xf bank_mask:0xf bound_ctrl:1
	v_add_f32_dpp v166, v166, v166 quad_perm:[1,0,3,2] row_mask:0xf bank_mask:0xf bound_ctrl:1
	v_add_f32_dpp v144, v144, v144 quad_perm:[2,3,0,1] row_mask:0xf bank_mask:0xf bound_ctrl:1
	v_add_f32_dpp v147, v147, v147 quad_perm:[2,3,0,1] row_mask:0xf bank_mask:0xf bound_ctrl:1
	v_add_f32_dpp v152, v152, v152 quad_perm:[2,3,0,1] row_mask:0xf bank_mask:0xf bound_ctrl:1
	v_add_f32_dpp v156, v156, v156 quad_perm:[2,3,0,1] row_mask:0xf bank_mask:0xf bound_ctrl:1
	v_add_f32_dpp v158, v158, v158 quad_perm:[2,3,0,1] row_mask:0xf bank_mask:0xf bound_ctrl:1
	v_add_f32_dpp v160, v160, v160 quad_perm:[2,3,0,1] row_mask:0xf bank_mask:0xf bound_ctrl:1
	v_add_f32_dpp v162, v162, v162 quad_perm:[2,3,0,1] row_mask:0xf bank_mask:0xf bound_ctrl:1
	v_add_f32_dpp v164, v164, v164 quad_perm:[2,3,0,1] row_mask:0xf bank_mask:0xf bound_ctrl:1
	v_add_f32_dpp v166, v166, v166 quad_perm:[2,3,0,1] row_mask:0xf bank_mask:0xf bound_ctrl:1
	v_add_f32_dpp v144, v144, v144 row_half_mirror row_mask:0xf bank_mask:0xf bound_ctrl:1
	v_add_f32_dpp v147, v147, v147 row_half_mirror row_mask:0xf bank_mask:0xf bound_ctrl:1
	v_add_f32_dpp v152, v152, v152 row_half_mirror row_mask:0xf bank_mask:0xf bound_ctrl:1
	v_add_f32_dpp v156, v156, v156 row_half_mirror row_mask:0xf bank_mask:0xf bound_ctrl:1
	v_add_f32_dpp v158, v158, v158 row_half_mirror row_mask:0xf bank_mask:0xf bound_ctrl:1
	v_add_f32_dpp v160, v160, v160 row_half_mirror row_mask:0xf bank_mask:0xf bound_ctrl:1
	v_add_f32_dpp v162, v162, v162 row_half_mirror row_mask:0xf bank_mask:0xf bound_ctrl:1
	v_add_f32_dpp v164, v164, v164 row_half_mirror row_mask:0xf bank_mask:0xf bound_ctrl:1
	v_add_f32_dpp v166, v166, v166 row_half_mirror row_mask:0xf bank_mask:0xf bound_ctrl:1
	v_add_f32_dpp v144, v144, v144 row_mirror row_mask:0xf bank_mask:0xf bound_ctrl:1
	v_add_f32_dpp v147, v147, v147 row_mirror row_mask:0xf bank_mask:0xf bound_ctrl:1
	v_add_f32_dpp v152, v152, v152 row_mirror row_mask:0xf bank_mask:0xf bound_ctrl:1
	v_add_f32_dpp v156, v156, v156 row_mirror row_mask:0xf bank_mask:0xf bound_ctrl:1
	v_add_f32_dpp v158, v158, v158 row_mirror row_mask:0xf bank_mask:0xf bound_ctrl:1
	v_add_f32_dpp v160, v160, v160 row_mirror row_mask:0xf bank_mask:0xf bound_ctrl:1
	v_add_f32_dpp v162, v162, v162 row_mirror row_mask:0xf bank_mask:0xf bound_ctrl:1
	v_add_f32_dpp v164, v164, v164 row_mirror row_mask:0xf bank_mask:0xf bound_ctrl:1
	v_add_f32_dpp v166, v166, v166 row_mirror row_mask:0xf bank_mask:0xf bound_ctrl:1
	v_mov_b32_e32 v153, v144
	v_mov_b32_e32 v154, v147
	v_mov_b32_e32 v155, v152
	v_mov_b32_e32 v157, v156
	v_mov_b32_e32 v159, v158
	v_mov_b32_e32 v161, v160
	v_mov_b32_e32 v163, v162
	v_mov_b32_e32 v165, v164
	v_mov_b32_e32 v167, v166
	v_permlane16_swap_b32_e32 v144, v153
	v_permlane16_swap_b32_e32 v147, v154
	v_permlane16_swap_b32_e32 v152, v155
	v_permlane16_swap_b32_e32 v156, v157
	v_permlane16_swap_b32_e32 v158, v159
	v_permlane16_swap_b32_e32 v160, v161
	v_permlane16_swap_b32_e32 v162, v163
	v_permlane16_swap_b32_e32 v164, v165
	v_permlane16_swap_b32_e32 v166, v167
	v_add_f32_e32 v144, v144, v153
	v_add_f32_e32 v147, v147, v154
	v_add_f32_e32 v153, v152, v155
	v_add_f32_e32 v156, v156, v157
	v_add_f32_e32 v158, v158, v159
	v_add_f32_e32 v160, v160, v161
	v_add_f32_e32 v162, v162, v163
	v_add_f32_e32 v164, v164, v165
	v_add_f32_e32 v166, v166, v167
	v_mov_b32_e32 v152, v144
	v_mov_b32_e32 v154, v147
	v_mov_b32_e32 v155, v153
	v_mov_b32_e32 v157, v156
	v_mov_b32_e32 v159, v158
	v_mov_b32_e32 v161, v160
	v_mov_b32_e32 v163, v162
	v_mov_b32_e32 v165, v164
	v_mov_b32_e32 v167, v166
	v_permlane32_swap_b32_e32 v144, v152
	v_permlane32_swap_b32_e32 v147, v154
	v_permlane32_swap_b32_e32 v153, v155
	v_permlane32_swap_b32_e32 v156, v157
	v_permlane32_swap_b32_e32 v158, v159
	v_permlane32_swap_b32_e32 v160, v161
	v_permlane32_swap_b32_e32 v162, v163
	v_permlane32_swap_b32_e32 v164, v165
	v_permlane32_swap_b32_e32 v166, v167
	s_and_saveexec_b64 s[68:69], s[4:5]
	s_cbranch_execz .LBB0_104
	v_add_f32_e32 v144, v144, v152
	v_add_co_u32_e32 v152, vcc, 0xffff0000, v148
	v_add_f32_e32 v155, v153, v155
	s_nop 0
	v_addc_co_u32_e32 v153, vcc, -1, v149, vcc
	global_store_dword v[152:153], v144, off
	v_add_co_u32_e32 v152, vcc, 0xffff2000, v148
	v_add_f32_e32 v147, v147, v154
	s_nop 0
	v_addc_co_u32_e32 v153, vcc, -1, v149, vcc
	global_store_dword v[152:153], v147, off
	v_add_co_u32_e32 v152, vcc, 0xffff4000, v148
	v_add_f32_e32 v156, v156, v157
	s_nop 0
	v_addc_co_u32_e32 v153, vcc, -1, v149, vcc
	global_store_dword v[152:153], v155, off
	v_add_co_u32_e32 v152, vcc, 0xffff6000, v148
	v_add_f32_e32 v158, v158, v159
	s_nop 0
	v_addc_co_u32_e32 v153, vcc, -1, v149, vcc
	global_store_dword v[152:153], v156, off
	v_add_co_u32_e32 v152, vcc, 0xffff8000, v148
	v_add_f32_e32 v160, v160, v161
	s_nop 0
	v_addc_co_u32_e32 v153, vcc, -1, v149, vcc
	global_store_dword v[152:153], v158, off
	v_add_co_u32_e32 v152, vcc, 0xffffa000, v148
	v_add_f32_e32 v162, v162, v163
	s_nop 0
	v_addc_co_u32_e32 v153, vcc, -1, v149, vcc
	global_store_dword v[152:153], v160, off
	v_add_co_u32_e32 v152, vcc, 0xffffc000, v148
	v_add_f32_e32 v164, v164, v165
	s_nop 0
	v_addc_co_u32_e32 v153, vcc, -1, v149, vcc
	global_store_dword v[152:153], v162, off
	v_add_co_u32_e32 v152, vcc, 0xffffe000, v148
	v_add_f32_e32 v166, v166, v167
	s_nop 0
	v_addc_co_u32_e32 v153, vcc, -1, v149, vcc
	global_store_dword v[152:153], v164, off
	global_store_dword v[148:149], v166, off
	s_branch .LBB0_104

.LBB0_108:
	s_waitcnt vmcnt(0)
	s_or_b64 exec, exec, s[42:43]
	s_add_i32 s55, s55, 1
	s_add_u32 s10, s10, 0x31800
	s_addc_u32 s11, s11, 0
	s_add_u32 s12, s12, 0xb00000
	s_addc_u32 s13, s13, 0
	s_cmp_eq_u32 s55, 4
	s_cbranch_scc1 .LBB0_114
.LBB0_109:
	s_mov_b64 s[4:5], s[26:27]
	s_mov_b64 s[46:47], s[26:27]
	s_mov_b64 s[44:45], s[26:27]
	v_mov_b32_e32 v0, v179
	s_nop 0
	v_ashrrev_i32_e32 v1, 6, v0
	v_add_u32_e32 v146, s89, v1
	v_cmp_gt_i32_e32 vcc, s2, v146
	s_and_saveexec_b64 s[42:43], vcc
	s_cbranch_execz .LBB0_108
	v_and_b32_e32 v152, 63, v0
	v_lshlrev_b32_e32 v144, 6, v152
	v_lshl_add_u64 v[0:1], s[4:5], 0, v[144:145]
	s_mul_i32 s8, s55, 0x36000
	v_lshl_add_u64 v[128:129], v[0:1], 0, s[8:9]
	v_add_co_u32_e32 v8, vcc, 0x103000, v128
	v_lshl_add_u64 v[12:13], v[128:129], 0, s[14:15]
	s_nop 0
	v_addc_co_u32_e32 v9, vcc, 0, v129, vcc
	v_add_co_u32_e32 v24, vcc, s3, v128
	v_lshl_add_u64 v[28:29], v[128:129], 0, s[16:17]
	s_nop 0
	v_addc_co_u32_e32 v25, vcc, 0, v129, vcc
	v_add_co_u32_e32 v40, vcc, s24, v128
	v_lshl_add_u64 v[44:45], v[128:129], 0, s[18:19]
	s_nop 0
	v_addc_co_u32_e32 v41, vcc, 0, v129, vcc
	v_add_co_u32_e32 v56, vcc, s25, v128
	v_lshl_add_u64 v[60:61], v[128:129], 0, s[20:21]
	s_nop 0
	v_addc_co_u32_e32 v57, vcc, 0, v129, vcc
	v_add_co_u32_e32 v72, vcc, s33, v128
	v_lshl_add_u64 v[76:77], v[128:129], 0, s[22:23]
	s_nop 0
	v_addc_co_u32_e32 v73, vcc, 0, v129, vcc
	v_add_co_u32_e32 v88, vcc, s50, v128
	v_lshl_add_u64 v[92:93], v[128:129], 0, s[28:29]
	s_nop 0
	v_addc_co_u32_e32 v89, vcc, 0, v129, vcc
	v_add_co_u32_e32 v104, vcc, s51, v128
	v_lshl_add_u64 v[108:109], v[128:129], 0, s[34:35]
	s_nop 0
	v_addc_co_u32_e32 v105, vcc, 0, v129, vcc
	v_add_co_u32_e32 v120, vcc, s52, v128
	v_lshl_add_u64 v[124:125], v[128:129], 0, s[36:37]
	s_nop 0
	v_addc_co_u32_e32 v121, vcc, 0, v129, vcc
	v_add_co_u32_e32 v136, vcc, s53, v128
	v_lshl_add_u64 v[140:141], v[128:129], 0, s[38:39]
	s_nop 0
	v_addc_co_u32_e32 v137, vcc, 0, v129, vcc
	global_load_dwordx4 v[0:3], v[12:13], off offset:16
	global_load_dwordx4 v[4:7], v[12:13], off offset:32
	s_nop 0
	global_load_dwordx4 v[8:11], v[8:9], off
	s_nop 0
	global_load_dwordx4 v[12:15], v[12:13], off offset:48
	s_nop 0
	global_load_dwordx4 v[16:19], v[28:29], off offset:16
	global_load_dwordx4 v[20:23], v[28:29], off offset:32
	s_nop 0
	global_load_dwordx4 v[24:27], v[24:25], off
	s_nop 0
	global_load_dwordx4 v[28:31], v[28:29], off offset:48
	s_nop 0
	global_load_dwordx4 v[32:35], v[44:45], off offset:16
	global_load_dwordx4 v[36:39], v[44:45], off offset:32
	s_nop 0
	global_load_dwordx4 v[40:43], v[40:41], off
	s_nop 0
	global_load_dwordx4 v[44:47], v[44:45], off offset:48
	s_nop 0
	global_load_dwordx4 v[48:51], v[60:61], off offset:16
	global_load_dwordx4 v[52:55], v[60:61], off offset:32
	s_nop 0
	global_load_dwordx4 v[56:59], v[56:57], off
	s_nop 0
	global_load_dwordx4 v[60:63], v[60:61], off offset:48
	s_nop 0
	global_load_dwordx4 v[64:67], v[76:77], off offset:16
	global_load_dwordx4 v[68:71], v[76:77], off offset:32
	s_nop 0
	global_load_dwordx4 v[72:75], v[72:73], off
	s_nop 0
	global_load_dwordx4 v[76:79], v[76:77], off offset:48
	s_nop 0
	global_load_dwordx4 v[80:83], v[92:93], off offset:16
	global_load_dwordx4 v[84:87], v[92:93], off offset:32
	s_nop 0
	global_load_dwordx4 v[88:91], v[88:89], off
	s_nop 0
	global_load_dwordx4 v[92:95], v[92:93], off offset:48
	s_nop 0
	global_load_dwordx4 v[96:99], v[108:109], off offset:16
	global_load_dwordx4 v[100:103], v[108:109], off offset:32
	s_nop 0
	global_load_dwordx4 v[104:107], v[104:105], off
	s_nop 0
	global_load_dwordx4 v[108:111], v[108:109], off offset:48
	s_nop 0
	global_load_dwordx4 v[112:115], v[124:125], off offset:16
	global_load_dwordx4 v[116:119], v[124:125], off offset:32
	s_nop 0
	global_load_dwordx4 v[120:123], v[120:121], off
	s_nop 0
	global_load_dwordx4 v[124:127], v[124:125], off offset:48
	s_nop 0
	global_load_dwordx4 v[128:131], v[140:141], off offset:16
	global_load_dwordx4 v[132:135], v[140:141], off offset:32
	s_nop 0
	global_load_dwordx4 v[136:139], v[136:137], off
	s_nop 0
	global_load_dwordx4 v[140:143], v[140:141], off offset:48
	v_ashrrev_i32_e32 v147, 31, v146
	v_lshlrev_b64 v[150:151], 11, v[146:147]
	v_lshl_add_u64 v[150:151], s[12:13], 0, v[150:151]
	v_lshlrev_b32_e32 v144, 5, v152
	s_add_u32 s44, s44, s10
	v_lshl_add_u64 v[150:151], v[150:151], 0, v[144:145]
	v_cmp_eq_u32_e64 s[4:5], 0, v152
	v_lshlrev_b64 v[148:149], 2, v[146:147]
	s_addc_u32 s45, s45, s11
	v_lshl_add_u64 v[150:151], s[46:47], 0, v[150:151]
	s_mov_b64 s[46:47], 0
	v_add_co_u32_e32 v242, vcc, 0x2f00000, v150
	v_lshl_add_u64 v[244:245], v[150:151], 0, s[40:41]
	s_nop 0
	v_addc_co_u32_e32 v243, vcc, 0, v151, vcc
	global_load_dwordx4 v[232:235], v[242:243], off
	global_load_dwordx4 v[236:239], v[244:245], off offset:16
	s_waitcnt vmcnt(0)
	s_branch .LBB0_112

.LBB0_112:
	s_waitcnt vmcnt(9)
	v_mov_b64_e32 v[152:153], v[232:233]
	v_mov_b64_e32 v[154:155], v[234:235]
	v_mov_b64_e32 v[156:157], v[236:237]
	v_mov_b64_e32 v[158:159], v[238:239]
	v_lshl_add_u64 v[240:241], v[150:151], 0, s[90:91]
	v_add_co_u32_e32 v242, vcc, 0x2f00000, v240
	v_lshl_add_u64 v[244:245], v[240:241], 0, s[40:41]
	s_nop 0
	v_addc_co_u32_e32 v243, vcc, 0, v241, vcc
	global_load_dwordx4 v[232:235], v[242:243], off
	global_load_dwordx4 v[236:239], v[244:245], off offset:16
	v_lshlrev_b32_e32 v166, 16, v152
	v_and_b32_e32 v167, 0xffff0000, v152
	v_lshlrev_b32_e32 v174, 16, v156
	v_and_b32_e32 v175, 0xffff0000, v156
	v_lshlrev_b32_e32 v178, 16, v158
	v_and_b32_e32 v180, 0xffff0000, v158
	v_fma_f32 v144, v8, v166, 0
	v_fma_f32 v147, v24, v166, 0
	v_fma_f32 v152, v40, v166, 0
	v_fma_f32 v156, v56, v166, 0
	v_fma_f32 v158, v72, v166, 0
	v_fma_f32 v160, v88, v166, 0
	v_fma_f32 v162, v104, v166, 0
	v_fma_f32 v164, v120, v166, 0
	v_fma_f32 v166, v136, v166, 0
	v_lshlrev_b32_e32 v168, 16, v153
	v_fmac_f32_e32 v144, v9, v167
	v_fmac_f32_e32 v147, v25, v167
	v_fmac_f32_e32 v152, v41, v167
	v_fmac_f32_e32 v156, v57, v167
	v_fmac_f32_e32 v158, v73, v167
	v_fmac_f32_e32 v160, v89, v167
	v_fmac_f32_e32 v162, v105, v167
	v_fmac_f32_e32 v164, v121, v167
	v_fmac_f32_e32 v166, v137, v167
	v_and_b32_e32 v169, 0xffff0000, v153
	v_fmac_f32_e32 v144, v10, v168
	v_fmac_f32_e32 v147, v26, v168
	v_fmac_f32_e32 v152, v42, v168
	v_fmac_f32_e32 v156, v58, v168
	v_fmac_f32_e32 v158, v74, v168
	v_fmac_f32_e32 v160, v90, v168
	v_fmac_f32_e32 v162, v106, v168
	v_fmac_f32_e32 v164, v122, v168
	v_fmac_f32_e32 v166, v138, v168
	v_lshlrev_b32_e32 v170, 16, v154
	v_fmac_f32_e32 v144, v11, v169
	v_fmac_f32_e32 v147, v27, v169
	v_fmac_f32_e32 v152, v43, v169
	v_fmac_f32_e32 v156, v59, v169
	v_fmac_f32_e32 v158, v75, v169
	v_fmac_f32_e32 v160, v91, v169
	v_fmac_f32_e32 v162, v107, v169
	v_fmac_f32_e32 v164, v123, v169
	v_fmac_f32_e32 v166, v139, v169
	v_and_b32_e32 v171, 0xffff0000, v154
	v_fmac_f32_e32 v144, v0, v170
	v_fmac_f32_e32 v147, v16, v170
	v_fmac_f32_e32 v152, v32, v170
	v_fmac_f32_e32 v156, v48, v170
	v_fmac_f32_e32 v158, v64, v170
	v_fmac_f32_e32 v160, v80, v170
	v_fmac_f32_e32 v162, v96, v170
	v_fmac_f32_e32 v164, v112, v170
	v_fmac_f32_e32 v166, v128, v170
	v_lshlrev_b32_e32 v172, 16, v155
	v_fmac_f32_e32 v144, v1, v171
	v_fmac_f32_e32 v147, v17, v171
	v_fmac_f32_e32 v152, v33, v171
	v_fmac_f32_e32 v156, v49, v171
	v_fmac_f32_e32 v158, v65, v171
	v_fmac_f32_e32 v160, v81, v171
	v_fmac_f32_e32 v162, v97, v171
	v_fmac_f32_e32 v164, v113, v171
	v_fmac_f32_e32 v166, v129, v171
	v_and_b32_e32 v173, 0xffff0000, v155
	v_fmac_f32_e32 v144, v2, v172
	v_fmac_f32_e32 v147, v18, v172
	v_fmac_f32_e32 v152, v34, v172
	v_fmac_f32_e32 v156, v50, v172
	v_fmac_f32_e32 v158, v66, v172
	v_fmac_f32_e32 v160, v82, v172
	v_fmac_f32_e32 v162, v98, v172
	v_fmac_f32_e32 v164, v114, v172
	v_fmac_f32_e32 v166, v130, v172
	v_fmac_f32_e32 v144, v3, v173
	v_fmac_f32_e32 v147, v19, v173
	v_fmac_f32_e32 v152, v35, v173
	v_fmac_f32_e32 v156, v51, v173
	v_fmac_f32_e32 v158, v67, v173
	v_fmac_f32_e32 v160, v83, v173
	v_fmac_f32_e32 v162, v99, v173
	v_fmac_f32_e32 v164, v115, v173
	v_fmac_f32_e32 v166, v131, v173
	v_fmac_f32_e32 v144, v4, v174
	v_fmac_f32_e32 v147, v20, v174
	v_fmac_f32_e32 v152, v36, v174
	v_fmac_f32_e32 v156, v52, v174
	v_fmac_f32_e32 v158, v68, v174
	v_fmac_f32_e32 v160, v84, v174
	v_fmac_f32_e32 v162, v100, v174
	v_fmac_f32_e32 v164, v116, v174
	v_fmac_f32_e32 v166, v132, v174
	v_lshlrev_b32_e32 v176, 16, v157
	v_fmac_f32_e32 v144, v5, v175
	v_fmac_f32_e32 v147, v21, v175
	v_fmac_f32_e32 v152, v37, v175
	v_fmac_f32_e32 v156, v53, v175
	v_fmac_f32_e32 v158, v69, v175
	v_fmac_f32_e32 v160, v85, v175
	v_fmac_f32_e32 v162, v101, v175
	v_fmac_f32_e32 v164, v117, v175
	v_fmac_f32_e32 v166, v133, v175
	v_and_b32_e32 v177, 0xffff0000, v157
	v_fmac_f32_e32 v144, v6, v176
	v_fmac_f32_e32 v147, v22, v176
	v_fmac_f32_e32 v152, v38, v176
	v_fmac_f32_e32 v156, v54, v176
	v_fmac_f32_e32 v158, v70, v176
	v_fmac_f32_e32 v160, v86, v176
	v_fmac_f32_e32 v162, v102, v176
	v_fmac_f32_e32 v164, v118, v176
	v_fmac_f32_e32 v166, v134, v176
	v_fmac_f32_e32 v144, v7, v177
	v_fmac_f32_e32 v147, v23, v177
	v_fmac_f32_e32 v152, v39, v177
	v_fmac_f32_e32 v156, v55, v177
	v_fmac_f32_e32 v158, v71, v177
	v_fmac_f32_e32 v160, v87, v177
	v_fmac_f32_e32 v162, v103, v177
	v_fmac_f32_e32 v164, v119, v177
	v_fmac_f32_e32 v166, v135, v177
	v_fmac_f32_e32 v144, v12, v178
	v_fmac_f32_e32 v147, v28, v178
	v_fmac_f32_e32 v152, v44, v178
	v_fmac_f32_e32 v156, v60, v178
	v_fmac_f32_e32 v158, v76, v178
	v_fmac_f32_e32 v160, v92, v178
	v_fmac_f32_e32 v162, v108, v178
	v_fmac_f32_e32 v164, v124, v178
	v_fmac_f32_e32 v166, v140, v178
	v_lshlrev_b32_e32 v181, 16, v159
	v_fmac_f32_e32 v144, v13, v180
	v_fmac_f32_e32 v147, v29, v180
	v_fmac_f32_e32 v152, v45, v180
	v_fmac_f32_e32 v156, v61, v180
	v_fmac_f32_e32 v158, v77, v180
	v_fmac_f32_e32 v160, v93, v180
	v_fmac_f32_e32 v162, v109, v180
	v_fmac_f32_e32 v164, v125, v180
	v_fmac_f32_e32 v166, v141, v180
	v_and_b32_e32 v182, 0xffff0000, v159
	v_fmac_f32_e32 v144, v14, v181
	v_fmac_f32_e32 v147, v30, v181
	v_fmac_f32_e32 v152, v46, v181
	v_fmac_f32_e32 v156, v62, v181
	v_fmac_f32_e32 v158, v78, v181
	v_fmac_f32_e32 v160, v94, v181
	v_fmac_f32_e32 v162, v110, v181
	v_fmac_f32_e32 v164, v126, v181
	v_fmac_f32_e32 v166, v142, v181
	v_fmac_f32_e32 v144, v15, v182
	v_fmac_f32_e32 v147, v31, v182
	v_fmac_f32_e32 v152, v47, v182
	v_fmac_f32_e32 v156, v63, v182
	v_fmac_f32_e32 v158, v79, v182
	v_fmac_f32_e32 v160, v95, v182
	v_fmac_f32_e32 v162, v111, v182
	v_fmac_f32_e32 v164, v127, v182
	v_fmac_f32_e32 v166, v143, v182
	v_add_f32_dpp v144, v144, v144 quad_perm:[1,0,3,2] row_mask:0xf bank_mask:0xf bound_ctrl:1
	v_add_f32_dpp v147, v147, v147 quad_perm:[1,0,3,2] row_mask:0xf bank_mask:0xf bound_ctrl:1
	v_add_f32_dpp v152, v152, v152 quad_perm:[1,0,3,2] row_mask:0xf bank_mask:0xf bound_ctrl:1
	v_add_f32_dpp v156, v156, v156 quad_perm:[1,0,3,2] row_mask:0xf bank_mask:0xf bound_ctrl:1
	v_add_f32_dpp v158, v158, v158 quad_perm:[1,0,3,2] row_mask:0xf bank_mask:0xf bound_ctrl:1
	v_add_f32_dpp v160, v160, v160 quad_perm:[1,0,3,2] row_mask:0xf bank_mask:0xf bound_ctrl:1
	v_add_f32_dpp v162, v162, v162 quad_perm:[1,0,3,2] row_mask:0xf bank_mask:0xf bound_ctrl:1
	v_add_f32_dpp v164, v164, v164 quad_perm:[1,0,3,2] row_mask:0xf bank_mask:0xf bound_ctrl:1
	v_add_f32_dpp v166, v166, v166 quad_perm:[1,0,3,2] row_mask:0xf bank_mask:0xf bound_ctrl:1
	v_add_f32_dpp v144, v144, v144 quad_perm:[2,3,0,1] row_mask:0xf bank_mask:0xf bound_ctrl:1
	v_add_f32_dpp v147, v147, v147 quad_perm:[2,3,0,1] row_mask:0xf bank_mask:0xf bound_ctrl:1
	v_add_f32_dpp v152, v152, v152 quad_perm:[2,3,0,1] row_mask:0xf bank_mask:0xf bound_ctrl:1
	v_add_f32_dpp v156, v156, v156 quad_perm:[2,3,0,1] row_mask:0xf bank_mask:0xf bound_ctrl:1
	v_add_f32_dpp v158, v158, v158 quad_perm:[2,3,0,1] row_mask:0xf bank_mask:0xf bound_ctrl:1
	v_add_f32_dpp v160, v160, v160 quad_perm:[2,3,0,1] row_mask:0xf bank_mask:0xf bound_ctrl:1
	v_add_f32_dpp v162, v162, v162 quad_perm:[2,3,0,1] row_mask:0xf bank_mask:0xf bound_ctrl:1
	v_add_f32_dpp v164, v164, v164 quad_perm:[2,3,0,1] row_mask:0xf bank_mask:0xf bound_ctrl:1
	v_add_f32_dpp v166, v166, v166 quad_perm:[2,3,0,1] row_mask:0xf bank_mask:0xf bound_ctrl:1
	v_add_f32_dpp v144, v144, v144 row_half_mirror row_mask:0xf bank_mask:0xf bound_ctrl:1
	v_add_f32_dpp v147, v147, v147 row_half_mirror row_mask:0xf bank_mask:0xf bound_ctrl:1
	v_add_f32_dpp v152, v152, v152 row_half_mirror row_mask:0xf bank_mask:0xf bound_ctrl:1
	v_add_f32_dpp v156, v156, v156 row_half_mirror row_mask:0xf bank_mask:0xf bound_ctrl:1
	v_add_f32_dpp v158, v158, v158 row_half_mirror row_mask:0xf bank_mask:0xf bound_ctrl:1
	v_add_f32_dpp v160, v160, v160 row_half_mirror row_mask:0xf bank_mask:0xf bound_ctrl:1
	v_add_f32_dpp v162, v162, v162 row_half_mirror row_mask:0xf bank_mask:0xf bound_ctrl:1
	v_add_f32_dpp v164, v164, v164 row_half_mirror row_mask:0xf bank_mask:0xf bound_ctrl:1
	v_add_f32_dpp v166, v166, v166 row_half_mirror row_mask:0xf bank_mask:0xf bound_ctrl:1
	v_add_f32_dpp v144, v144, v144 row_mirror row_mask:0xf bank_mask:0xf bound_ctrl:1
	v_add_f32_dpp v147, v147, v147 row_mirror row_mask:0xf bank_mask:0xf bound_ctrl:1
	v_add_f32_dpp v152, v152, v152 row_mirror row_mask:0xf bank_mask:0xf bound_ctrl:1
	v_add_f32_dpp v156, v156, v156 row_mirror row_mask:0xf bank_mask:0xf bound_ctrl:1
	v_add_f32_dpp v158, v158, v158 row_mirror row_mask:0xf bank_mask:0xf bound_ctrl:1
	v_add_f32_dpp v160, v160, v160 row_mirror row_mask:0xf bank_mask:0xf bound_ctrl:1
	v_add_f32_dpp v162, v162, v162 row_mirror row_mask:0xf bank_mask:0xf bound_ctrl:1
	v_add_f32_dpp v164, v164, v164 row_mirror row_mask:0xf bank_mask:0xf bound_ctrl:1
	v_add_f32_dpp v166, v166, v166 row_mirror row_mask:0xf bank_mask:0xf bound_ctrl:1
	v_mov_b32_e32 v153, v144
	v_mov_b32_e32 v154, v147
	v_mov_b32_e32 v155, v152
	v_mov_b32_e32 v157, v156
	v_mov_b32_e32 v159, v158
	v_mov_b32_e32 v161, v160
	v_mov_b32_e32 v163, v162
	v_mov_b32_e32 v165, v164
	v_mov_b32_e32 v167, v166
	v_permlane16_swap_b32_e32 v144, v153
	v_permlane16_swap_b32_e32 v147, v154
	v_permlane16_swap_b32_e32 v152, v155
	v_permlane16_swap_b32_e32 v156, v157
	v_permlane16_swap_b32_e32 v158, v159
	v_permlane16_swap_b32_e32 v160, v161
	v_permlane16_swap_b32_e32 v162, v163
	v_permlane16_swap_b32_e32 v164, v165
	v_permlane16_swap_b32_e32 v166, v167
	v_add_f32_e32 v144, v144, v153
	v_add_f32_e32 v147, v147, v154
	v_add_f32_e32 v153, v152, v155
	v_add_f32_e32 v156, v156, v157
	v_add_f32_e32 v158, v158, v159
	v_add_f32_e32 v160, v160, v161
	v_add_f32_e32 v162, v162, v163
	v_add_f32_e32 v164, v164, v165
	v_add_f32_e32 v166, v166, v167
	v_mov_b32_e32 v152, v144
	v_mov_b32_e32 v154, v147
	v_mov_b32_e32 v155, v153
	v_mov_b32_e32 v157, v156
	v_mov_b32_e32 v159, v158
	v_mov_b32_e32 v161, v160
	v_mov_b32_e32 v163, v162
	v_mov_b32_e32 v165, v164
	v_mov_b32_e32 v167, v166
	v_permlane32_swap_b32_e32 v144, v152
	v_permlane32_swap_b32_e32 v147, v154
	v_permlane32_swap_b32_e32 v153, v155
	v_permlane32_swap_b32_e32 v156, v157
	v_permlane32_swap_b32_e32 v158, v159
	v_permlane32_swap_b32_e32 v160, v161
	v_permlane32_swap_b32_e32 v162, v163
	v_permlane32_swap_b32_e32 v164, v165
	v_permlane32_swap_b32_e32 v166, v167
	s_and_saveexec_b64 s[48:49], s[4:5]
	s_cbranch_execz .LBB0_111
	v_add_f32_e32 v156, v156, v157
	v_add_f32_e32 v157, v153, v155
	v_add_f32_e32 v144, v144, v152
	v_lshl_add_u64 v[152:153], s[44:45], 0, v[148:149]
	v_add_f32_e32 v147, v147, v154
	v_add_co_u32_e32 v154, vcc, 0xfffd4000, v152
	v_add_f32_e32 v158, v158, v159
	s_nop 0
	v_addc_co_u32_e32 v155, vcc, -1, v153, vcc
	global_store_dword v[154:155], v144, off
	v_add_co_u32_e32 v154, vcc, 0xfffda000, v152
	v_add_f32_e32 v160, v160, v161
	s_nop 0
	v_addc_co_u32_e32 v155, vcc, -1, v153, vcc
	global_store_dword v[154:155], v147, off offset:-2048
	v_add_co_u32_e32 v154, vcc, 0xfffdf000, v152
	v_add_f32_e32 v162, v162, v163
	s_nop 0
	v_addc_co_u32_e32 v155, vcc, -1, v153, vcc
	global_store_dword v[154:155], v157, off
	v_add_co_u32_e32 v154, vcc, 0xfffe5000, v152
	v_add_f32_e32 v164, v164, v165
	s_nop 0
	v_addc_co_u32_e32 v155, vcc, -1, v153, vcc
	global_store_dword v[154:155], v156, off offset:-2048
	v_add_co_u32_e32 v154, vcc, 0xfffea000, v152
	v_add_f32_e32 v166, v166, v167
	s_nop 0
	v_addc_co_u32_e32 v155, vcc, -1, v153, vcc
	global_store_dword v[154:155], v158, off
	v_add_co_u32_e32 v154, vcc, 0xffff0000, v152
	s_nop 1
	v_addc_co_u32_e32 v155, vcc, -1, v153, vcc
	global_store_dword v[154:155], v160, off offset:-2048
	v_add_co_u32_e32 v154, vcc, 0xffff5000, v152
	s_nop 1
	v_addc_co_u32_e32 v155, vcc, -1, v153, vcc
	global_store_dword v[154:155], v162, off
	v_add_co_u32_e32 v154, vcc, 0xffffb000, v152
	s_nop 1
	v_addc_co_u32_e32 v155, vcc, -1, v153, vcc
	global_store_dword v[154:155], v164, off offset:-2048
	global_store_dword v[152:153], v166, off
	s_branch .LBB0_111
